# on top of v25: write-through (sc1) also on phase-0 residual-init stores and the weight-transpose stores (full-line writes that precede grid barriers)
# speedup vs baseline: 1.0102x; 1.0102x over previous
; #define LAS __attribute__((address_space(3)))
; #define GAS __attribute__((address_space(1)))
; __device__ __forceinline__ unsigned pk2(float lo, float hi) { const f32x2_t v = {lo, hi}; const bf16x2_t b = __builtin_convertvector(v, bf16x2_t); return __builtin_bit_cast(unsigned, b); }
; __device__ __forceinline__ void transpose_item(const GAS float* W, int K, int N, const GAS float* gain, GAS bf16* WT, LAS float* scr, int item, int lane, int remap) {
;     ...
;     const int c = lane & 7;
; #pragma unroll
;     for (int j = 0; j < 4; ++j) { const int n = (lane >> 3) + 8 * j; const LAS float* s = scr + (8 * c) * 33 + n;
;         v4u o; o.x = pk2(s[0 * 33], s[1 * 33]); o.y = pk2(s[2 * 33], s[3 * 33]); o.z = pk2(s[4 * 33], s[5 * 33]); o.w = pk2(s[6 * 33], s[7 * 33]);
;         *(GAS v4u*)(WT + (size_t)(n0 + n) * K + k0 + 8 * c) = o; }
;     asm volatile("s_waitcnt lgkmcnt(0)" ::: "memory");
.LBB0_9:
	s_waitcnt lgkmcnt(0)
	ds_read2_b32 v[18:19], v36 offset0:33 offset1:41
	ds_read2_b32 v[20:21], v36 offset1:8
	ds_read2_b32 v[22:23], v36 offset0:66 offset1:74
	ds_read2_b32 v[24:25], v36 offset0:99 offset1:107
	ds_read2_b32 v[26:27], v36 offset0:132 offset1:140
	ds_read2_b32 v[28:29], v36 offset0:165 offset1:173
	ds_read2_b32 v[30:31], v36 offset0:198 offset1:206
	ds_read2_b32 v[32:33], v36 offset0:231 offset1:239
	v_or_b32_e32 v48, s18, v7
	v_ashrrev_i32_e32 v49, 31, v48
	v_lshl_add_u64 v[34:35], s[6:7], 1, v[8:9]
	v_lshlrev_b64 v[48:49], 11, v[48:49]
	s_waitcnt lgkmcnt(6)
	v_cvt_pk_bf16_f32 v14, v20, v18
	s_waitcnt lgkmcnt(4)
	v_cvt_pk_bf16_f32 v15, v22, v24
	s_waitcnt lgkmcnt(2)
	v_cvt_pk_bf16_f32 v16, v26, v28
	s_waitcnt lgkmcnt(0)
	v_cvt_pk_bf16_f32 v17, v30, v32
	v_lshl_add_u64 v[48:49], v[34:35], 0, v[48:49]
	v_or_b32_e32 v18, s18, v37
	global_store_dwordx4 v[48:49], v[14:17], off sc1
	s_nop 1
	v_cvt_pk_bf16_f32 v14, v21, v19
	v_ashrrev_i32_e32 v19, 31, v18
	v_cvt_pk_bf16_f32 v15, v23, v25
	v_cvt_pk_bf16_f32 v16, v27, v29
	v_cvt_pk_bf16_f32 v17, v31, v33
	v_lshlrev_b64 v[18:19], 11, v[18:19]
	ds_read2_b32 v[20:21], v36 offset0:49 offset1:57
	ds_read2_b32 v[22:23], v36 offset0:16 offset1:24
	ds_read2_b32 v[24:25], v36 offset0:82 offset1:90
	ds_read2_b32 v[26:27], v36 offset0:115 offset1:123
	ds_read2_b32 v[28:29], v36 offset0:148 offset1:156
	ds_read2_b32 v[30:31], v36 offset0:181 offset1:189
	ds_read2_b32 v[32:33], v36 offset0:214 offset1:222
	ds_read2_b32 v[48:49], v36 offset0:247 offset1:255
	v_lshl_add_u64 v[18:19], v[34:35], 0, v[18:19]
	global_store_dwordx4 v[18:19], v[14:17], off sc1
	v_or_b32_e32 v18, s18, v38
	v_ashrrev_i32_e32 v19, 31, v18
	v_lshlrev_b64 v[18:19], 11, v[18:19]
	s_waitcnt lgkmcnt(6)
	v_cvt_pk_bf16_f32 v14, v22, v20
	s_waitcnt lgkmcnt(4)
	v_cvt_pk_bf16_f32 v15, v24, v26
	s_waitcnt lgkmcnt(2)
	v_cvt_pk_bf16_f32 v16, v28, v30
	s_waitcnt lgkmcnt(0)
	v_cvt_pk_bf16_f32 v17, v32, v48
	v_lshl_add_u64 v[18:19], v[34:35], 0, v[18:19]
	global_store_dwordx4 v[18:19], v[14:17], off sc1
	v_or_b32_e32 v18, s18, v39
	v_ashrrev_i32_e32 v19, 31, v18
	v_lshlrev_b64 v[18:19], 11, v[18:19]
	v_cvt_pk_bf16_f32 v14, v23, v21
	v_cvt_pk_bf16_f32 v15, v25, v27
	v_cvt_pk_bf16_f32 v16, v29, v31
	v_cvt_pk_bf16_f32 v17, v33, v49
	v_lshl_add_u64 v[18:19], v[34:35], 0, v[18:19]
	global_store_dwordx4 v[18:19], v[14:17], off sc1
	s_waitcnt lgkmcnt(0)

; __device__ __forceinline__ void transpose_item(const GAS float* W, int K, int N, const GAS float* gain, GAS bf16* WT, LAS float* scr, int item, int lane, int remap) {
;     ...
;     for (int i = 0; i < 32; ++i) { const int kk = 2 * i + (lane >> 5); float w = W[(size_t)(k0 + kk) * N + ns + (lane & 31)]; if (gain) w *= gain[k0 + kk]; scr[kk * 33 + (lane & 31)] = w; }
.LBB0_14:
	s_lshl_b32 s11, s8, 1
	s_lshl_b32 s10, s5, 1
	v_or_b32_e32 v50, s11, v2
	s_add_i32 s13, s11, 4
	s_add_i32 s12, s10, 4
	s_add_i32 s18, s10, 8
	s_add_i32 s19, s11, 8
	v_add_u32_e32 v112, s6, v50
	v_or_b32_e32 v52, s13, v2
	v_or_b32_e32 v13, s10, v1
	s_add_i32 s20, s10, 12
	s_add_i32 s21, s11, 12
	s_add_i32 s22, s10, 16
	s_add_i32 s24, s10, 20
	s_add_i32 s26, s10, 24
	s_add_i32 s10, s10, 28
	v_or_b32_e32 v51, s12, v1
	v_or_b32_e32 v53, s18, v1
	v_or_b32_e32 v54, s19, v2
	v_lshlrev_b64 v[32:33], 12, v[112:113]
	v_add_u32_e32 v112, s6, v52
	v_mov_b32_e32 v17, v113
	v_mov_b32_e32 v19, v113
	v_mov_b32_e32 v21, v113
	s_add_i32 s23, s11, 16
	v_add_u32_e32 v16, s7, v13
	v_or_b32_e32 v55, s20, v1
	v_or_b32_e32 v56, s21, v2
	v_or_b32_e32 v57, s22, v1
	v_or_b32_e32 v59, s24, v1
	v_or_b32_e32 v61, s26, v1
	v_or_b32_e32 v63, s10, v1
	v_add_u32_e32 v18, s7, v51
	v_add_u32_e32 v20, s7, v53
	v_lshlrev_b64 v[34:35], 12, v[112:113]
	v_add_u32_e32 v112, s6, v54
	v_mov_b32_e32 v23, v113
	v_mov_b32_e32 v25, v113
	v_mov_b32_e32 v27, v113
	v_mov_b32_e32 v29, v113
	v_mov_b32_e32 v31, v113
	s_add_i32 s25, s11, 20
	v_or_b32_e32 v58, s23, v2
	v_lshlrev_b64 v[16:17], 12, v[16:17]
	v_add_u32_e32 v22, s7, v55
	v_add_u32_e32 v24, s7, v57
	v_add_u32_e32 v26, s7, v59
	v_add_u32_e32 v28, s7, v61
	v_add_u32_e32 v30, s7, v63
	v_lshl_add_u64 v[32:33], v[14:15], 0, v[32:33]
	v_lshlrev_b64 v[18:19], 12, v[18:19]
	v_lshlrev_b64 v[20:21], 12, v[20:21]
	v_lshlrev_b64 v[48:49], 12, v[112:113]
	v_add_u32_e32 v112, s6, v56
	s_add_i32 s27, s11, 24
	v_or_b32_e32 v60, s25, v2
	v_lshl_add_u64 v[16:17], v[14:15], 0, v[16:17]
	v_lshlrev_b64 v[22:23], 12, v[22:23]
	v_lshlrev_b64 v[24:25], 12, v[24:25]
	v_lshlrev_b64 v[26:27], 12, v[26:27]
	v_lshlrev_b64 v[28:29], 12, v[28:29]
	v_lshlrev_b64 v[30:31], 12, v[30:31]
	v_lshl_add_u64 v[34:35], v[14:15], 0, v[34:35]
	v_lshl_add_u64 v[18:19], v[14:15], 0, v[18:19]
	v_lshl_add_u64 v[20:21], v[14:15], 0, v[20:21]
	global_load_dword v65, v[32:33], off
	global_load_dword v66, v[16:17], off
	v_lshlrev_b64 v[32:33], 12, v[112:113]
	v_add_u32_e32 v112, s6, v58
	s_add_i32 s11, s11, 28
	v_or_b32_e32 v62, s27, v2
	v_lshl_add_u64 v[22:23], v[14:15], 0, v[22:23]
	v_lshl_add_u64 v[24:25], v[14:15], 0, v[24:25]
	v_lshl_add_u64 v[26:27], v[14:15], 0, v[26:27]
	v_lshl_add_u64 v[28:29], v[14:15], 0, v[28:29]
	v_lshl_add_u64 v[30:31], v[14:15], 0, v[30:31]
	global_load_dword v67, v[34:35], off
	global_load_dword v68, v[18:19], off
	global_load_dword v69, v[20:21], off
	global_load_dword v70, v[22:23], off
	global_load_dword v71, v[24:25], off
	global_load_dword v72, v[26:27], off
	global_load_dword v73, v[28:29], off
	global_load_dword v74, v[30:31], off
	v_lshl_add_u64 v[18:19], v[14:15], 0, v[32:33]
	v_lshlrev_b64 v[20:21], 12, v[112:113]
	v_add_u32_e32 v112, s6, v60
	v_or_b32_e32 v64, s11, v2
	v_lshl_add_u64 v[16:17], v[14:15], 0, v[48:49]
	global_load_dword v75, v[18:19], off
	global_load_dword v76, v[16:17], off
	v_lshlrev_b64 v[18:19], 12, v[112:113]
	v_add_u32_e32 v112, s6, v62
	v_lshl_add_u64 v[16:17], v[14:15], 0, v[20:21]
	v_lshlrev_b64 v[20:21], 12, v[112:113]
	v_add_u32_e32 v112, s6, v64
	v_lshlrev_b64 v[22:23], 12, v[112:113]
	v_lshl_add_u64 v[22:23], v[14:15], 0, v[22:23]
	v_lshl_add_u64 v[18:19], v[14:15], 0, v[18:19]
	v_lshl_add_u64 v[20:21], v[14:15], 0, v[20:21]
	global_load_dword v77, v[22:23], off
	global_load_dword v78, v[20:21], off
	global_load_dword v79, v[18:19], off
	global_load_dword v80, v[16:17], off
	s_add_i32 s8, s8, 16
	s_add_i32 s5, s5, 16
	s_add_i32 s9, s9, -16
	v_mad_u64_u32 v[16:17], s[10:11], v50, s95, v[6:7]
	s_cmp_lg_u32 s9, 0
	v_mad_u64_u32 v[18:19], s[10:11], v13, s95, v[6:7]
	v_mad_u64_u32 v[20:21], s[10:11], v52, s95, v[6:7]
	v_mad_u64_u32 v[22:23], s[10:11], v51, s95, v[6:7]
	v_mad_u64_u32 v[24:25], s[10:11], v54, s95, v[6:7]
	v_mad_u64_u32 v[26:27], s[10:11], v53, s95, v[6:7]
	v_mad_u64_u32 v[28:29], s[10:11], v56, s95, v[6:7]
	v_mad_u64_u32 v[30:31], s[10:11], v55, s95, v[6:7]
	v_mad_u64_u32 v[32:33], s[10:11], v58, s95, v[6:7]
	v_mad_u64_u32 v[34:35], s[10:11], v57, s95, v[6:7]
	v_mad_u64_u32 v[48:49], s[10:11], v60, s95, v[6:7]
	v_mad_u64_u32 v[50:51], s[10:11], v59, s95, v[6:7]
	v_mad_u64_u32 v[52:53], s[10:11], v62, s95, v[6:7]
	v_mad_u64_u32 v[54:55], s[10:11], v61, s95, v[6:7]
	v_mad_u64_u32 v[56:57], s[10:11], v64, s95, v[6:7]
	v_mad_u64_u32 v[58:59], s[10:11], v63, s95, v[6:7]
	s_waitcnt vmcnt(0)
	ds_write_b32 v16, v65
	ds_write_b32 v18, v66
	ds_write_b32 v20, v67
	ds_write_b32 v22, v68
	ds_write_b32 v24, v76
	ds_write_b32 v26, v69
	ds_write_b32 v28, v75
	ds_write_b32 v30, v70
	ds_write_b32 v32, v80
	ds_write_b32 v34, v71
	ds_write_b32 v48, v79
	ds_write_b32 v50, v72
	ds_write_b32 v52, v78
	ds_write_b32 v54, v73
	ds_write_b32 v56, v77
	ds_write_b32 v58, v74
	s_cbranch_scc1 .LBB0_14
; #define LAS __attribute__((address_space(3)))
; #define GAS __attribute__((address_space(1)))
; __device__ __forceinline__ unsigned pk2(float lo, float hi) { const f32x2_t v = {lo, hi}; const bf16x2_t b = __builtin_convertvector(v, bf16x2_t); return __builtin_bit_cast(unsigned, b); }
; __device__ __forceinline__ void transpose_item(const GAS float* W, int K, int N, const GAS float* gain, GAS bf16* WT, LAS float* scr, int item, int lane, int remap) {
;     ...
;     const int c = lane & 7;
; #pragma unroll
;     for (int j = 0; j < 4; ++j) { const int n = (lane >> 3) + 8 * j; const LAS float* s = scr + (8 * c) * 33 + n;
;         v4u o; o.x = pk2(s[0 * 33], s[1 * 33]); o.y = pk2(s[2 * 33], s[3 * 33]); o.z = pk2(s[4 * 33], s[5 * 33]); o.w = pk2(s[6 * 33], s[7 * 33]);
;         *(GAS v4u*)(WT + (size_t)(n0 + n) * K + k0 + 8 * c) = o; }
;     asm volatile("s_waitcnt lgkmcnt(0)" ::: "memory");
	s_waitcnt lgkmcnt(0)
	ds_read2_b32 v[18:19], v36 offset0:33 offset1:41
	ds_read2_b32 v[20:21], v36 offset1:8
	ds_read2_b32 v[22:23], v36 offset0:66 offset1:74
	ds_read2_b32 v[24:25], v36 offset0:99 offset1:107
	ds_read2_b32 v[26:27], v36 offset0:132 offset1:140
	ds_read2_b32 v[28:29], v36 offset0:165 offset1:173
	ds_read2_b32 v[30:31], v36 offset0:198 offset1:206
	ds_read2_b32 v[32:33], v36 offset0:231 offset1:239
	s_lshl_b32 s60, s6, 1
	v_or_b32_e32 v13, s4, v7
	v_lshl_add_u64 v[34:35], v[10:11], 0, s[60:61]
	v_lshlrev_b32_e32 v112, 12, v13
	s_waitcnt lgkmcnt(6)
	v_cvt_pk_bf16_f32 v14, v20, v18
	s_waitcnt lgkmcnt(4)
	v_cvt_pk_bf16_f32 v15, v22, v24
	s_waitcnt lgkmcnt(2)
	v_cvt_pk_bf16_f32 v16, v26, v28
	s_waitcnt lgkmcnt(0)
	v_cvt_pk_bf16_f32 v17, v30, v32
	v_lshl_add_u64 v[48:49], v[34:35], 0, v[112:113]
	global_store_dwordx4 v[48:49], v[14:17], off sc1
	v_or_b32_e32 v13, s4, v37
	v_lshlrev_b32_e32 v112, 12, v13
	v_cvt_pk_bf16_f32 v14, v21, v19
	v_cvt_pk_bf16_f32 v15, v23, v25
	v_cvt_pk_bf16_f32 v16, v27, v29
	v_cvt_pk_bf16_f32 v17, v31, v33
	ds_read2_b32 v[20:21], v36 offset0:49 offset1:57
	ds_read2_b32 v[22:23], v36 offset0:16 offset1:24
	ds_read2_b32 v[24:25], v36 offset0:82 offset1:90
	ds_read2_b32 v[26:27], v36 offset0:115 offset1:123
	ds_read2_b32 v[28:29], v36 offset0:148 offset1:156
	ds_read2_b32 v[30:31], v36 offset0:181 offset1:189
	ds_read2_b32 v[32:33], v36 offset0:214 offset1:222
	ds_read2_b32 v[48:49], v36 offset0:247 offset1:255
	v_or_b32_e32 v13, s4, v38
	v_lshl_add_u64 v[18:19], v[34:35], 0, v[112:113]
	v_lshlrev_b32_e32 v112, 12, v13
	v_or_b32_e32 v13, s4, v39
	global_store_dwordx4 v[18:19], v[14:17], off sc1
	v_lshl_add_u64 v[18:19], v[34:35], 0, v[112:113]
	v_lshlrev_b32_e32 v112, 12, v13
	s_waitcnt lgkmcnt(6)
	v_cvt_pk_bf16_f32 v14, v22, v20
	s_waitcnt lgkmcnt(4)
	v_cvt_pk_bf16_f32 v15, v24, v26
	s_waitcnt lgkmcnt(2)
	v_cvt_pk_bf16_f32 v16, v28, v30
	s_waitcnt lgkmcnt(0)
	v_cvt_pk_bf16_f32 v17, v32, v48
	global_store_dwordx4 v[18:19], v[14:17], off sc1
	v_lshl_add_u64 v[18:19], v[34:35], 0, v[112:113]
	s_nop 0
	v_cvt_pk_bf16_f32 v14, v23, v21
	v_cvt_pk_bf16_f32 v15, v25, v27
	v_cvt_pk_bf16_f32 v16, v29, v31
	v_cvt_pk_bf16_f32 v17, v33, v49
	global_store_dwordx4 v[18:19], v[14:17], off sc1
	s_waitcnt lgkmcnt(0)
	s_branch .LBB0_10

; #define GAS __attribute__((address_space(1)))
; __device__ __forceinline__ unsigned pk2(float lo, float hi) { const f32x2_t v = {lo, hi}; const bf16x2_t b = __builtin_convertvector(v, bf16x2_t); return __builtin_bit_cast(unsigned, b); }
; __device__ __forceinline__ void init_rows(const GAS float* x, GAS bf16* xres, GAS float* ssq, int nrows, int gw, int ngw, int lane) {
;     for (int m0 = 2 * gw; m0 < nrows; m0 += 2 * ngw) {
;         f32x4 v[2][4];
; #pragma unroll
;         for (int q = 0; q < 2; ++q) { const GAS f32x4* xr = (const GAS f32x4*)(x + (size_t)(m0 + q) * D) + lane;
; #pragma unroll
;             for (int j = 0; j < 4; ++j) v[q][j] = xr[64 * j]; }
; #pragma unroll
;         for (int q = 0; q < 2; ++q) { float s = 0.f; GAS unsigned long long* o8 = (GAS unsigned long long*)(xres + (size_t)(m0 + q) * D) + lane;
; #pragma unroll
;             for (int j = 0; j < 4; ++j) { const unsigned w0 = pk2(v[q][j].x, v[q][j].y), w1 = pk2(v[q][j].z, v[q][j].w); o8[64 * j] = (unsigned long long)w0 | ((unsigned long long)w1 << 32);
;                 const float a0 = __uint_as_float(w0 << 16), a1 = __uint_as_float(w0 & 0xffff0000u), a2 = __uint_as_float(w1 << 16), a3 = __uint_as_float(w1 & 0xffff0000u); s += (a0 * a0 + a1 * a1) + (a2 * a2 + a3 * a3); }
;             s = wave_sum(s);
;             if (lane < 16) ssq[(size_t)(m0 + q) * 16 + lane] = (lane == 0) ? s : 0.f; }
.LBB0_37:
	global_load_dwordx4 v[28:31], v[18:19], off offset:-4096
	v_add_co_u32_e32 v0, vcc, 0xfffff000, v18
	s_waitcnt vmcnt(0)
	v_cvt_pk_bf16_f32 v45, v30, v31
	s_waitcnt lgkmcnt(0)
	v_addc_co_u32_e32 v1, vcc, -1, v19, vcc
	global_load_dwordx4 v[32:35], v[0:1], off offset:-3072
	global_load_dwordx4 v[36:39], v[0:1], off offset:-2048
	global_load_dwordx4 v[40:43], v[0:1], off offset:-1024
	global_load_dwordx4 v[12:15], v[18:19], off offset:-3072
	global_load_dwordx4 v[8:11], v[18:19], off offset:-2048
	global_load_dwordx4 v[4:7], v[18:19], off offset:-1024
	s_nop 0
	global_load_dwordx4 v[0:3], v[18:19], off
	v_cvt_pk_bf16_f32 v44, v28, v29
	v_and_b32_e32 v30, 0xffff0000, v45
	v_and_b32_e32 v29, 0xffff0000, v44
	v_mul_f32_e32 v47, v30, v30
	v_lshlrev_b32_e32 v28, 16, v44
	v_lshlrev_b32_e32 v46, 16, v45
	v_mul_f32_e32 v29, v29, v29
	v_fmac_f32_e32 v29, v28, v28
	v_fmac_f32_e32 v47, v46, v46
	v_add_f32_e32 v29, v29, v47
	s_waitcnt vmcnt(6)
	v_cvt_pk_bf16_f32 v30, v32, v33
	v_cvt_pk_bf16_f32 v31, v34, v35
	s_waitcnt vmcnt(5)
	v_cvt_pk_bf16_f32 v32, v36, v37
	v_cvt_pk_bf16_f32 v33, v38, v39
	s_waitcnt vmcnt(4)
	v_cvt_pk_bf16_f32 v34, v40, v41
	v_cvt_pk_bf16_f32 v35, v42, v43
	v_and_b32_e32 v36, 0xffff0000, v30
	v_and_b32_e32 v38, 0xffff0000, v31
	v_and_b32_e32 v40, 0xffff0000, v32
	v_and_b32_e32 v42, 0xffff0000, v33
	v_lshlrev_b32_e32 v28, 16, v30
	v_lshlrev_b32_e32 v37, 16, v31
	v_lshlrev_b32_e32 v39, 16, v32
	v_lshlrev_b32_e32 v41, 16, v33
	v_and_b32_e32 v46, 0xffff0000, v34
	v_and_b32_e32 v49, 0xffff0000, v35
	v_mul_f32_e32 v36, v36, v36
	v_mul_f32_e32 v38, v38, v38
	v_mul_f32_e32 v40, v40, v40
	v_mul_f32_e32 v42, v42, v42
	v_lshlrev_b32_e32 v43, 16, v34
	v_lshlrev_b32_e32 v48, 16, v35
	v_mul_f32_e32 v46, v46, v46
	v_mul_f32_e32 v49, v49, v49
	v_fmac_f32_e32 v36, v28, v28
	v_fmac_f32_e32 v38, v37, v37
	v_fmac_f32_e32 v40, v39, v39
	v_fmac_f32_e32 v42, v41, v41
	v_fmac_f32_e32 v46, v43, v43
	v_fmac_f32_e32 v49, v48, v48
	v_add_f32_e32 v28, v36, v38
	v_add_f32_e32 v36, v40, v42
	v_add_f32_e32 v37, v46, v49
	v_add_f32_e32 v28, v28, v36
	v_add_f32_e32 v28, v28, v37
	v_add_f32_e32 v28, v28, v29
	ds_bpermute_b32 v29, v22, v28
	global_store_dwordx2 v[20:21], v[30:31], off offset:-2048 sc1
	global_store_dwordx2 v[20:21], v[32:33], off offset:-1536 sc1
	global_store_dwordx2 v[20:21], v[34:35], off offset:-1024 sc1
	global_store_dwordx2 v[20:21], v[44:45], off offset:-512 sc1
	s_waitcnt lgkmcnt(0)
	v_add_f32_e32 v28, v28, v29
	ds_bpermute_b32 v29, v23, v28
	s_waitcnt lgkmcnt(0)
	v_add_f32_e32 v28, v28, v29
	ds_bpermute_b32 v29, v24, v28
	s_waitcnt lgkmcnt(0)
	v_add_f32_e32 v28, v28, v29
	ds_bpermute_b32 v29, v25, v28
	s_waitcnt lgkmcnt(0)
	v_add_f32_e32 v28, v28, v29
	ds_bpermute_b32 v29, v26, v28
	s_waitcnt lgkmcnt(0)
	v_add_f32_e32 v28, v28, v29
	ds_bpermute_b32 v29, v27, v28
	s_and_saveexec_b64 s[0:1], s[4:5]
	s_cbranch_execz .LBB0_39
	s_waitcnt lgkmcnt(0)
	v_add_f32_e32 v28, v28, v29
	v_cndmask_b32_e64 v28, 0, v28, s[6:7]
	global_store_dword v[16:17], v28, off offset:-64
.LBB0_39:
	s_or_b64 exec, exec, s[0:1]
	s_waitcnt vmcnt(7)
	v_cvt_pk_bf16_f32 v12, v12, v13
	v_cvt_pk_bf16_f32 v13, v14, v15
	v_and_b32_e32 v15, 0xffff0000, v12
	v_lshlrev_b32_e32 v14, 16, v12
	s_waitcnt lgkmcnt(0)
	v_and_b32_e32 v29, 0xffff0000, v13
	v_mul_f32_e32 v15, v15, v15
	s_waitcnt vmcnt(6)
	v_cvt_pk_bf16_f32 v8, v8, v9
	v_lshlrev_b32_e32 v28, 16, v13
	v_fmac_f32_e32 v15, v14, v14
	v_mul_f32_e32 v14, v29, v29
	v_cvt_pk_bf16_f32 v9, v10, v11
	v_and_b32_e32 v11, 0xffff0000, v8
	v_fmac_f32_e32 v14, v28, v28
	v_lshlrev_b32_e32 v10, 16, v8
	v_and_b32_e32 v28, 0xffff0000, v9
	v_mul_f32_e32 v11, v11, v11
	v_add_f32_e32 v14, v15, v14
	v_lshlrev_b32_e32 v15, 16, v9
	v_fmac_f32_e32 v11, v10, v10
	v_mul_f32_e32 v10, v28, v28
	v_fmac_f32_e32 v10, v15, v15
	s_waitcnt vmcnt(5)
	v_cvt_pk_bf16_f32 v4, v4, v5
	v_add_f32_e32 v10, v11, v10
	v_cvt_pk_bf16_f32 v5, v6, v7
	v_and_b32_e32 v7, 0xffff0000, v4
	v_add_f32_e32 v10, v14, v10
	v_lshlrev_b32_e32 v6, 16, v4
	v_and_b32_e32 v14, 0xffff0000, v5
	v_mul_f32_e32 v7, v7, v7
	v_lshlrev_b32_e32 v11, 16, v5
	v_fmac_f32_e32 v7, v6, v6
	v_mul_f32_e32 v6, v14, v14
	v_fmac_f32_e32 v6, v11, v11
	v_add_f32_e32 v6, v7, v6
	v_add_f32_e32 v10, v10, v6
	s_waitcnt vmcnt(4)
	v_cvt_pk_bf16_f32 v6, v0, v1
	v_cvt_pk_bf16_f32 v7, v2, v3
	v_and_b32_e32 v1, 0xffff0000, v6
	v_lshlrev_b32_e32 v0, 16, v6
	v_and_b32_e32 v3, 0xffff0000, v7
	v_mul_f32_e32 v1, v1, v1
	v_lshlrev_b32_e32 v2, 16, v7
	v_fmac_f32_e32 v1, v0, v0
	v_mul_f32_e32 v0, v3, v3
	v_fmac_f32_e32 v0, v2, v2
	v_add_f32_e32 v0, v1, v0
	v_add_f32_e32 v0, v10, v0
	ds_bpermute_b32 v1, v22, v0
	global_store_dwordx2 v[20:21], v[12:13], off sc1
	global_store_dwordx2 v[20:21], v[8:9], off offset:512 sc1
	global_store_dwordx2 v[20:21], v[4:5], off offset:1024 sc1
	global_store_dwordx2 v[20:21], v[6:7], off offset:1536 sc1
	s_waitcnt lgkmcnt(0)
	v_add_f32_e32 v0, v0, v1
	ds_bpermute_b32 v1, v23, v0
	s_waitcnt lgkmcnt(0)
	v_add_f32_e32 v0, v0, v1
	ds_bpermute_b32 v1, v24, v0
	s_waitcnt lgkmcnt(0)
	v_add_f32_e32 v0, v0, v1
	ds_bpermute_b32 v1, v25, v0
	s_waitcnt lgkmcnt(0)
	v_add_f32_e32 v0, v0, v1
	ds_bpermute_b32 v1, v26, v0
	s_waitcnt lgkmcnt(0)
	v_add_f32_e32 v0, v0, v1
	ds_bpermute_b32 v1, v27, v0
	s_and_saveexec_b64 s[0:1], s[4:5]
	s_cbranch_execz .LBB0_36
	s_waitcnt lgkmcnt(0)
	v_add_f32_e32 v0, v0, v1
	v_cndmask_b32_e64 v0, 0, v0, s[6:7]
	global_store_dword v[16:17], v0, off
	s_branch .LBB0_36

; __device__ __forceinline__ void transpose_item(const GAS float* W, int K, int N, const GAS float* gain, GAS bf16* WT, LAS float* scr, int item, int lane, int remap) {
;     ...
;     for (int i = 0; i < 32; ++i) { const int kk = 2 * i + (lane >> 5); float w = W[(size_t)(k0 + kk) * N + ns + (lane & 31)]; if (gain) w *= gain[k0 + kk]; scr[kk * 33 + (lane & 31)] = w; }
.LBB0_206:
	s_lshl_b32 s9, s6, 1
	s_lshl_b32 s8, s5, 1
	v_or_b32_e32 v19, s9, v0
	v_or_b32_e32 v18, s8, v1
	v_add_u32_e32 v16, s4, v19
	v_add_u32_e32 v14, s1, v18
	v_ashrrev_i32_e32 v17, 31, v16
	v_ashrrev_i32_e32 v15, 31, v14
	v_lshlrev_b64 v[16:17], 12, v[16:17]
	v_lshlrev_b64 v[14:15], 12, v[14:15]
	v_lshl_add_u64 v[16:17], v[8:9], 0, v[16:17]
	v_lshl_add_u64 v[14:15], v[8:9], 0, v[14:15]
	global_load_dword v36, v[16:17], off
	global_load_dword v37, v[14:15], off
	s_add_i32 s11, s9, 4
	s_add_i32 s10, s8, 4
	v_or_b32_e32 v19, s11, v0
	v_or_b32_e32 v18, s10, v1
	v_add_u32_e32 v16, s4, v19
	v_add_u32_e32 v14, s1, v18
	v_ashrrev_i32_e32 v17, 31, v16
	v_ashrrev_i32_e32 v15, 31, v14
	v_lshlrev_b64 v[16:17], 12, v[16:17]
	v_lshlrev_b64 v[14:15], 12, v[14:15]
	v_lshl_add_u64 v[16:17], v[8:9], 0, v[16:17]
	v_lshl_add_u64 v[14:15], v[8:9], 0, v[14:15]
	global_load_dword v38, v[16:17], off
	global_load_dword v39, v[14:15], off
	s_add_i32 s11, s9, 8
	s_add_i32 s10, s8, 8
	v_or_b32_e32 v19, s11, v0
	v_or_b32_e32 v18, s10, v1
	v_add_u32_e32 v16, s4, v19
	v_add_u32_e32 v14, s1, v18
	v_ashrrev_i32_e32 v17, 31, v16
	v_ashrrev_i32_e32 v15, 31, v14
	v_lshlrev_b64 v[16:17], 12, v[16:17]
	v_lshlrev_b64 v[14:15], 12, v[14:15]
	v_lshl_add_u64 v[16:17], v[8:9], 0, v[16:17]
	v_lshl_add_u64 v[14:15], v[8:9], 0, v[14:15]
	global_load_dword v40, v[16:17], off
	global_load_dword v41, v[14:15], off
	s_add_i32 s11, s9, 12
	s_add_i32 s10, s8, 12
	v_or_b32_e32 v19, s11, v0
	v_or_b32_e32 v18, s10, v1
	v_add_u32_e32 v16, s4, v19
	v_add_u32_e32 v14, s1, v18
	v_ashrrev_i32_e32 v17, 31, v16
	v_ashrrev_i32_e32 v15, 31, v14
	v_lshlrev_b64 v[16:17], 12, v[16:17]
	v_lshlrev_b64 v[14:15], 12, v[14:15]
	v_lshl_add_u64 v[16:17], v[8:9], 0, v[16:17]
	v_lshl_add_u64 v[14:15], v[8:9], 0, v[14:15]
	global_load_dword v42, v[16:17], off
	global_load_dword v43, v[14:15], off
	s_add_i32 s11, s9, 16
	s_add_i32 s10, s8, 16
	v_or_b32_e32 v19, s11, v0
	v_or_b32_e32 v18, s10, v1
	v_add_u32_e32 v16, s4, v19
	v_add_u32_e32 v14, s1, v18
	v_ashrrev_i32_e32 v17, 31, v16
	v_ashrrev_i32_e32 v15, 31, v14
	v_lshlrev_b64 v[16:17], 12, v[16:17]
	v_lshlrev_b64 v[14:15], 12, v[14:15]
	v_lshl_add_u64 v[16:17], v[8:9], 0, v[16:17]
	v_lshl_add_u64 v[14:15], v[8:9], 0, v[14:15]
	global_load_dword v44, v[16:17], off
	global_load_dword v45, v[14:15], off
	s_add_i32 s11, s9, 20
	s_add_i32 s10, s8, 20
	v_or_b32_e32 v19, s11, v0
	v_or_b32_e32 v18, s10, v1
	v_add_u32_e32 v16, s4, v19
	v_add_u32_e32 v14, s1, v18
	v_ashrrev_i32_e32 v17, 31, v16
	v_ashrrev_i32_e32 v15, 31, v14
	v_lshlrev_b64 v[16:17], 12, v[16:17]
	v_lshlrev_b64 v[14:15], 12, v[14:15]
	v_lshl_add_u64 v[16:17], v[8:9], 0, v[16:17]
	v_lshl_add_u64 v[14:15], v[8:9], 0, v[14:15]
	global_load_dword v46, v[16:17], off
	global_load_dword v47, v[14:15], off
	s_add_i32 s11, s9, 24
	s_add_i32 s10, s8, 24
	v_or_b32_e32 v19, s11, v0
	v_or_b32_e32 v18, s10, v1
	v_add_u32_e32 v16, s4, v19
	v_add_u32_e32 v14, s1, v18
	v_ashrrev_i32_e32 v17, 31, v16
	v_ashrrev_i32_e32 v15, 31, v14
	v_lshlrev_b64 v[16:17], 12, v[16:17]
	v_lshlrev_b64 v[14:15], 12, v[14:15]
	v_lshl_add_u64 v[16:17], v[8:9], 0, v[16:17]
	v_lshl_add_u64 v[14:15], v[8:9], 0, v[14:15]
	global_load_dword v48, v[16:17], off
	global_load_dword v49, v[14:15], off
	s_add_i32 s11, s9, 28
	s_add_i32 s10, s8, 28
	v_or_b32_e32 v19, s11, v0
	v_or_b32_e32 v18, s10, v1
	v_add_u32_e32 v16, s4, v19
	v_add_u32_e32 v14, s1, v18
	v_ashrrev_i32_e32 v17, 31, v16
	v_ashrrev_i32_e32 v15, 31, v14
	v_lshlrev_b64 v[16:17], 12, v[16:17]
	v_lshlrev_b64 v[14:15], 12, v[14:15]
	v_lshl_add_u64 v[16:17], v[8:9], 0, v[16:17]
	v_lshl_add_u64 v[14:15], v[8:9], 0, v[14:15]
	global_load_dword v50, v[16:17], off
	global_load_dword v51, v[14:15], off
	v_or_b32_e32 v19, s9, v0
	v_or_b32_e32 v18, s8, v1
	v_mad_u64_u32 v[14:15], s[10:11], v19, s95, v[4:5]
	v_mad_u64_u32 v[16:17], s[10:11], v18, s95, v[4:5]
	s_waitcnt vmcnt(14)
	ds_write_b32 v14, v36
	ds_write_b32 v16, v37
	s_add_i32 s11, s9, 4
	s_add_i32 s10, s8, 4
	v_or_b32_e32 v19, s11, v0
	v_or_b32_e32 v18, s10, v1
	v_mad_u64_u32 v[14:15], s[10:11], v19, s95, v[4:5]
	v_mad_u64_u32 v[16:17], s[10:11], v18, s95, v[4:5]
	s_waitcnt vmcnt(12)
	ds_write_b32 v14, v38
	ds_write_b32 v16, v39
	s_add_i32 s11, s9, 8
	s_add_i32 s10, s8, 8
	v_or_b32_e32 v19, s11, v0
	v_or_b32_e32 v18, s10, v1
	v_mad_u64_u32 v[14:15], s[10:11], v19, s95, v[4:5]
	v_mad_u64_u32 v[16:17], s[10:11], v18, s95, v[4:5]
	s_waitcnt vmcnt(10)
	ds_write_b32 v14, v40
	ds_write_b32 v16, v41
	s_add_i32 s11, s9, 12
	s_add_i32 s10, s8, 12
	v_or_b32_e32 v19, s11, v0
	v_or_b32_e32 v18, s10, v1
	v_mad_u64_u32 v[14:15], s[10:11], v19, s95, v[4:5]
	v_mad_u64_u32 v[16:17], s[10:11], v18, s95, v[4:5]
	s_waitcnt vmcnt(8)
	ds_write_b32 v14, v42
	ds_write_b32 v16, v43
	s_add_i32 s11, s9, 16
	s_add_i32 s10, s8, 16
	v_or_b32_e32 v19, s11, v0
	v_or_b32_e32 v18, s10, v1
	v_mad_u64_u32 v[14:15], s[10:11], v19, s95, v[4:5]
	v_mad_u64_u32 v[16:17], s[10:11], v18, s95, v[4:5]
	s_waitcnt vmcnt(6)
	ds_write_b32 v14, v44
	ds_write_b32 v16, v45
	s_add_i32 s11, s9, 20
	s_add_i32 s10, s8, 20
	v_or_b32_e32 v19, s11, v0
	v_or_b32_e32 v18, s10, v1
	v_mad_u64_u32 v[14:15], s[10:11], v19, s95, v[4:5]
	v_mad_u64_u32 v[16:17], s[10:11], v18, s95, v[4:5]
	s_waitcnt vmcnt(4)
	ds_write_b32 v14, v46
	ds_write_b32 v16, v47
	s_add_i32 s11, s9, 24
	s_add_i32 s10, s8, 24
	v_or_b32_e32 v19, s11, v0
	v_or_b32_e32 v18, s10, v1
	v_mad_u64_u32 v[14:15], s[10:11], v19, s95, v[4:5]
	v_mad_u64_u32 v[16:17], s[10:11], v18, s95, v[4:5]
	s_waitcnt vmcnt(2)
	ds_write_b32 v14, v48
	ds_write_b32 v16, v49
	s_add_i32 s11, s9, 28
	s_add_i32 s10, s8, 28
	v_or_b32_e32 v19, s11, v0
	v_or_b32_e32 v18, s10, v1
	v_mad_u64_u32 v[14:15], s[10:11], v19, s95, v[4:5]
	v_mad_u64_u32 v[16:17], s[10:11], v18, s95, v[4:5]
	s_waitcnt vmcnt(0)
	ds_write_b32 v14, v50
	ds_write_b32 v16, v51
	s_add_i32 s6, s6, 16
	s_add_i32 s5, s5, 16
	s_add_i32 s7, s7, -16
	s_cmp_lg_u32 s7, 0
	s_cbranch_scc1 .LBB0_206
; #define LAS __attribute__((address_space(3)))
; #define GAS __attribute__((address_space(1)))
; __device__ __forceinline__ unsigned pk2(float lo, float hi) { const f32x2_t v = {lo, hi}; const bf16x2_t b = __builtin_convertvector(v, bf16x2_t); return __builtin_bit_cast(unsigned, b); }
; __device__ __forceinline__ void transpose_item(const GAS float* W, int K, int N, const GAS float* gain, GAS bf16* WT, LAS float* scr, int item, int lane, int remap) {
;     ...
;     const int c = lane & 7;
; #pragma unroll
;     for (int j = 0; j < 4; ++j) { const int n = (lane >> 3) + 8 * j; const LAS float* s = scr + (8 * c) * 33 + n;
;         v4u o; o.x = pk2(s[0 * 33], s[1 * 33]); o.y = pk2(s[2 * 33], s[3 * 33]); o.z = pk2(s[4 * 33], s[5 * 33]); o.w = pk2(s[6 * 33], s[7 * 33]);
;         *(GAS v4u*)(WT + (size_t)(n0 + n) * K + k0 + 8 * c) = o; }
;     asm volatile("s_waitcnt lgkmcnt(0)" ::: "memory");
; __global__ void __launch_bounds__(512, 2) fwd(Args a) {
;     ...
;                 for (int it = c.gw; it < (MW / 64) * (D / 32); it += c.ngw) transpose_item(w_out, MW, D, nullptr, c.Wt_out, scr, it, c.lane, 0);
	s_waitcnt lgkmcnt(0)
	ds_read2_b32 v[18:19], v10 offset0:33 offset1:41
	ds_read2_b32 v[20:21], v10 offset1:8
	ds_read2_b32 v[22:23], v10 offset0:66 offset1:74
	ds_read2_b32 v[24:25], v10 offset0:99 offset1:107
	ds_read2_b32 v[26:27], v10 offset0:132 offset1:140
	ds_read2_b32 v[28:29], v10 offset0:165 offset1:173
	ds_read2_b32 v[30:31], v10 offset0:198 offset1:206
	ds_read2_b32 v[32:33], v10 offset0:231 offset1:239
	v_or_b32_e32 v34, s0, v5
	s_ashr_i32 s5, s4, 31
	v_ashrrev_i32_e32 v35, 31, v34
	v_lshl_add_u64 v[8:9], s[4:5], 1, v[6:7]
	v_lshlrev_b64 v[34:35], 12, v[34:35]
	s_waitcnt lgkmcnt(6)
	v_cvt_pk_bf16_f32 v14, v20, v18
	s_waitcnt lgkmcnt(4)
	v_cvt_pk_bf16_f32 v15, v22, v24
	s_waitcnt lgkmcnt(2)
	v_cvt_pk_bf16_f32 v16, v26, v28
	s_waitcnt lgkmcnt(0)
	v_cvt_pk_bf16_f32 v17, v30, v32
	v_lshl_add_u64 v[34:35], v[8:9], 0, v[34:35]
	v_or_b32_e32 v18, s0, v11
	global_store_dwordx4 v[34:35], v[14:17], off sc1
	v_or_b32_e32 v34, s0, v12
	v_ashrrev_i32_e32 v35, 31, v34
	v_cvt_pk_bf16_f32 v14, v21, v19
	v_ashrrev_i32_e32 v19, 31, v18
	v_lshlrev_b64 v[18:19], 12, v[18:19]
	v_cvt_pk_bf16_f32 v15, v23, v25
	v_cvt_pk_bf16_f32 v16, v27, v29
	v_cvt_pk_bf16_f32 v17, v31, v33
	v_lshl_add_u64 v[18:19], v[8:9], 0, v[18:19]
	global_store_dwordx4 v[18:19], v[14:17], off sc1
	ds_read2_b32 v[18:19], v10 offset0:49 offset1:57
	ds_read2_b32 v[20:21], v10 offset0:16 offset1:24
	ds_read2_b32 v[22:23], v10 offset0:82 offset1:90
	ds_read2_b32 v[24:25], v10 offset0:115 offset1:123
	ds_read2_b32 v[26:27], v10 offset0:148 offset1:156
	ds_read2_b32 v[28:29], v10 offset0:181 offset1:189
	ds_read2_b32 v[30:31], v10 offset0:214 offset1:222
	ds_read2_b32 v[32:33], v10 offset0:247 offset1:255
	v_lshlrev_b64 v[34:35], 12, v[34:35]
	s_waitcnt lgkmcnt(6)
	v_cvt_pk_bf16_f32 v14, v20, v18
	s_waitcnt lgkmcnt(4)
	v_cvt_pk_bf16_f32 v15, v22, v24
	s_waitcnt lgkmcnt(2)
	v_cvt_pk_bf16_f32 v16, v26, v28
	s_waitcnt lgkmcnt(0)
	v_cvt_pk_bf16_f32 v17, v30, v32
	v_lshl_add_u64 v[34:35], v[8:9], 0, v[34:35]
	v_or_b32_e32 v18, s0, v13
	global_store_dwordx4 v[34:35], v[14:17], off sc1
	s_add_i32 s3, s3, s33
	s_cmpk_lt_i32 s3, 0x400
	v_cvt_pk_bf16_f32 v14, v21, v19
	v_ashrrev_i32_e32 v19, 31, v18
	v_lshlrev_b64 v[18:19], 12, v[18:19]
	v_cvt_pk_bf16_f32 v15, v23, v25
	v_cvt_pk_bf16_f32 v16, v27, v29
	v_cvt_pk_bf16_f32 v17, v31, v33
	v_lshl_add_u64 v[8:9], v[8:9], 0, v[18:19]
	global_store_dwordx4 v[8:9], v[14:17], off sc1
	s_waitcnt lgkmcnt(0)
	s_cbranch_scc1 .LBB0_205

; #define LAS __attribute__((address_space(3)))
; #define GAS __attribute__((address_space(1)))
; __device__ __forceinline__ unsigned pk2(float lo, float hi) { const f32x2_t v = {lo, hi}; const bf16x2_t b = __builtin_convertvector(v, bf16x2_t); return __builtin_bit_cast(unsigned, b); }
; __device__ __forceinline__ void transpose_item(const GAS float* W, int K, int N, const GAS float* gain, GAS bf16* WT, LAS float* scr, int item, int lane, int remap) {
;     ...
;     const int c = lane & 7;
; #pragma unroll
;     for (int j = 0; j < 4; ++j) { const int n = (lane >> 3) + 8 * j; const LAS float* s = scr + (8 * c) * 33 + n;
;         v4u o; o.x = pk2(s[0 * 33], s[1 * 33]); o.y = pk2(s[2 * 33], s[3 * 33]); o.z = pk2(s[4 * 33], s[5 * 33]); o.w = pk2(s[6 * 33], s[7 * 33]);
;         *(GAS v4u*)(WT + (size_t)(n0 + n) * K + k0 + 8 * c) = o; }
;     asm volatile("s_waitcnt lgkmcnt(0)" ::: "memory");
; __global__ void __launch_bounds__(512, 2) fwd(Args a) {
;     ...
;                 for (int it = c.gw; it < (D / 64) * (PW / 32); it += c.ngw) transpose_item(w_in, D, PW, ln, c.Wt_in, scr, it, c.lane, nev);
.LBB0_651:
	s_waitcnt lgkmcnt(0)
	ds_read2_b32 v[12:13], v28 offset0:33 offset1:41
	ds_read2_b32 v[14:15], v28 offset1:8
	ds_read2_b32 v[16:17], v28 offset0:66 offset1:74
	ds_read2_b32 v[18:19], v28 offset0:99 offset1:107
	ds_read2_b32 v[20:21], v28 offset0:132 offset1:140
	ds_read2_b32 v[22:23], v28 offset0:165 offset1:173
	ds_read2_b32 v[24:25], v28 offset0:198 offset1:206
	ds_read2_b32 v[26:27], v28 offset0:231 offset1:239
	v_or_b32_e32 v40, s19, v1
	v_ashrrev_i32_e32 v41, 31, v40
	v_lshl_add_u64 v[10:11], s[12:13], 1, v[2:3]
	v_lshlrev_b64 v[40:41], 11, v[40:41]
	s_waitcnt lgkmcnt(6)
	v_cvt_pk_bf16_f32 v6, v14, v12
	s_waitcnt lgkmcnt(4)
	v_cvt_pk_bf16_f32 v7, v16, v18
	s_waitcnt lgkmcnt(2)
	v_cvt_pk_bf16_f32 v8, v20, v22
	s_waitcnt lgkmcnt(0)
	v_cvt_pk_bf16_f32 v9, v24, v26
	v_lshl_add_u64 v[40:41], v[10:11], 0, v[40:41]
	v_or_b32_e32 v12, s19, v29
	global_store_dwordx4 v[40:41], v[6:9], off sc1
	v_or_b32_e32 v40, s19, v30
	v_ashrrev_i32_e32 v41, 31, v40
	v_cvt_pk_bf16_f32 v6, v15, v13
	v_ashrrev_i32_e32 v13, 31, v12
	v_lshlrev_b64 v[12:13], 11, v[12:13]
	v_cvt_pk_bf16_f32 v7, v17, v19
	v_cvt_pk_bf16_f32 v8, v21, v23
	v_cvt_pk_bf16_f32 v9, v25, v27
	v_lshl_add_u64 v[12:13], v[10:11], 0, v[12:13]
	global_store_dwordx4 v[12:13], v[6:9], off sc1
	ds_read2_b32 v[12:13], v28 offset0:49 offset1:57
	ds_read2_b32 v[14:15], v28 offset0:16 offset1:24
	ds_read2_b32 v[16:17], v28 offset0:82 offset1:90
	ds_read2_b32 v[18:19], v28 offset0:115 offset1:123
	ds_read2_b32 v[20:21], v28 offset0:148 offset1:156
	ds_read2_b32 v[22:23], v28 offset0:181 offset1:189
	ds_read2_b32 v[24:25], v28 offset0:214 offset1:222
	ds_read2_b32 v[26:27], v28 offset0:247 offset1:255
	v_lshlrev_b64 v[40:41], 11, v[40:41]
	s_waitcnt lgkmcnt(6)
	v_cvt_pk_bf16_f32 v6, v14, v12
	s_waitcnt lgkmcnt(4)
	v_cvt_pk_bf16_f32 v7, v16, v18
	s_waitcnt lgkmcnt(2)
	v_cvt_pk_bf16_f32 v8, v20, v22
	s_waitcnt lgkmcnt(0)
	v_cvt_pk_bf16_f32 v9, v24, v26
	v_lshl_add_u64 v[40:41], v[10:11], 0, v[40:41]
	v_or_b32_e32 v12, s19, v31
	global_store_dwordx4 v[40:41], v[6:9], off sc1
	s_add_i32 s18, s18, s33
	s_cmpk_gt_i32 s18, 0xfff
	v_cvt_pk_bf16_f32 v6, v15, v13
	v_ashrrev_i32_e32 v13, 31, v12
	v_lshlrev_b64 v[12:13], 11, v[12:13]
	v_cvt_pk_bf16_f32 v7, v17, v19
	v_cvt_pk_bf16_f32 v8, v21, v23
	v_cvt_pk_bf16_f32 v9, v25, v27
	v_lshl_add_u64 v[10:11], v[10:11], 0, v[12:13]
	global_store_dwordx4 v[10:11], v[6:9], off sc1
	s_waitcnt lgkmcnt(0)
	s_cbranch_scc1 .LBB0_670
